# v28 with barrier protocol B + three staggered release-word polls in flight (results land in unused spill lanes, no drain at exit)
# speedup vs baseline: 1.0056x; 1.0056x over previous
; __device__ __forceinline__ unsigned xb_ld(unsigned* p)              { return __hip_atomic_load(p, __ATOMIC_RELAXED, __HIP_MEMORY_SCOPE_AGENT); }
; __device__ __forceinline__ unsigned xb_add(unsigned* p, unsigned v) { return __hip_atomic_fetch_add(p, v, __ATOMIC_RELAXED, __HIP_MEMORY_SCOPE_AGENT); }
; #define XB_SPIN(cond, bar) do { unsigned _sp = 0; while (cond) { __builtin_amdgcn_s_sleep(1); \
;     if ((++_sp & 255u) == 0u) { if (xb_ld(&(bar)[XB_TMO])) break; if (_sp > XB_SPIN_CAP) { atomicAdd(&(bar)[XB_TMO], 1u); break; } } } } while (0)
; __device__ __forceinline__ void xcd_barrier(const XcdBarrier& b, int wave) {
;     ...
;             else XB_SPIN(xb_ld(&bar[XB_TOPGEN]) == tg, bar);
;             __builtin_amdgcn_fence(__ATOMIC_ACQUIRE, "agent");
;             xb_add(&bar[XB_XGEN(b.x)], 1u);
;             asm volatile("s_waitcnt vmcnt(0)" ::: "memory");
;         } else {
;             XB_SPIN(xb_ld(&bar[XB_XGEN(b.x)]) == gen, bar);
;             __builtin_amdgcn_fence(__ATOMIC_ACQUIRE, "agent");
;             asm volatile("s_waitcnt vmcnt(0)" ::: "memory");
;         }
.Lxb_wait:
	v_readlane_b32 s4, v253, 53
	v_readlane_b32 s5, v253, 54
	v_readfirstlane_b32 s7, v7
	s_mov_b64 s[24:25], exec
	s_mov_b32 s2, 0
	s_nop 3
	s_mov_b32 exec_lo, 0
	s_mov_b32 exec_hi, 1
	global_load_dword v255, v1, s[4:5] sc1
	s_sleep 20
	s_mov_b32 exec_hi, 2
	global_load_dword v255, v1, s[4:5] sc1
	s_sleep 20
	s_mov_b32 exec_hi, 4
	global_load_dword v255, v1, s[4:5] sc1
.Lxb_spin:
	s_waitcnt vmcnt(2)
	v_readlane_b32 s6, v255, 32
	s_cmp_ge_u32 s6, s7
	s_cbranch_scc1 .Lxb_done
	s_mov_b32 exec_hi, 1
	global_load_dword v255, v1, s[4:5] sc1
	s_waitcnt vmcnt(2)
	v_readlane_b32 s6, v255, 33
	s_cmp_ge_u32 s6, s7
	s_cbranch_scc1 .Lxb_done
	s_mov_b32 exec_hi, 2
	global_load_dword v255, v1, s[4:5] sc1
	s_waitcnt vmcnt(2)
	v_readlane_b32 s6, v255, 34
	s_cmp_ge_u32 s6, s7
	s_cbranch_scc1 .Lxb_done
	s_mov_b32 exec_hi, 4
	global_load_dword v255, v1, s[4:5] sc1
	s_add_i32 s2, s2, 1
	s_cmp_lt_u32 s2, 0x20000
	s_cbranch_scc1 .Lxb_spin
.Lxb_done:
	s_mov_b64 exec, s[24:25]
	buffer_inv sc1
